# ffn1 output stores without sc0 sc1 (write-back; the other GEMMs keep write-through)
# baseline (speedup 1.0000x reference)
.Lgm_f1_dadv5:
	s_add_u32 s34, s34, 1
	s_add_u32 s31, s31, 1
	s_mov_b32 s4, 0xffff2000
	s_cmp_eq_u32 s40, 0
	s_cselect_b32 s4, 0xe000, s4
	s_cselect_b32 s40, 0xe000, 0
	v_add_u32_e32 v199, s4, v199
	v_add_u32_e32 v200, s4, v200
	v_add_u32_e32 v201, s4, v201
	v_add_u32_e32 v202, s4, v202
	s_cmp_lt_u32 s34, 16
	s_cbranch_scc1 .Lgm_f1_next
	s_and_b32 s6, s35, 31
	s_lshr_b32 s7, s35, 5
	s_mul_i32 s6, s6, 192
	s_lshl_b32 s7, s7, 8
	s_nop 7
	s_mul_i32 s4, s6, 0x2000
	s_lshl_b32 s5, s7, 1
	s_add_u32 s4, s4, s5
	v_add_u32_e32 v197, s4, v205
	ds_write_b32 v203, v4 offset:0
	ds_write_b32 v203, v5 offset:272
	ds_write_b32 v203, v6 offset:544
	ds_write_b32 v203, v7 offset:816
	ds_write_b32 v203, v8 offset:64
	ds_write_b32 v203, v9 offset:336
	ds_write_b32 v203, v10 offset:608
	ds_write_b32 v203, v11 offset:880
	ds_write_b32 v203, v12 offset:128
	ds_write_b32 v203, v13 offset:400
	ds_write_b32 v203, v14 offset:672
	ds_write_b32 v203, v15 offset:944
	ds_write_b32 v203, v16 offset:192
	ds_write_b32 v203, v17 offset:464
	ds_write_b32 v203, v18 offset:736
	ds_write_b32 v203, v19 offset:1008
	s_waitcnt lgkmcnt(0)
	ds_read_b128 v[156:159], v204 offset:0
	ds_read_b128 v[160:163], v204 offset:1088
	ds_read_b128 v[164:167], v204 offset:2176
	ds_read_b128 v[168:171], v204 offset:3264
	s_waitcnt lgkmcnt(3)
	v_max_f32_e32 v156, 0, v156
	v_max_f32_e32 v157, 0, v157
	v_max_f32_e32 v158, 0, v158
	v_max_f32_e32 v159, 0, v159
	v_mul_f32_e32 v156, v156, v156
	v_mul_f32_e32 v157, v157, v157
	v_mul_f32_e32 v158, v158, v158
	v_mul_f32_e32 v159, v159, v159
	v_cvt_pk_bf16_f32 v176, v156, v157
	v_cvt_pk_bf16_f32 v177, v158, v159
	global_store_dwordx2 v197, v[176:177], s[56:57]
	v_add_u32_e32 v197, 0x8000, v197
	s_waitcnt lgkmcnt(2)
	v_max_f32_e32 v160, 0, v160
	v_max_f32_e32 v161, 0, v161
	v_max_f32_e32 v162, 0, v162
	v_max_f32_e32 v163, 0, v163
	v_mul_f32_e32 v160, v160, v160
	v_mul_f32_e32 v161, v161, v161
	v_mul_f32_e32 v162, v162, v162
	v_mul_f32_e32 v163, v163, v163
	v_cvt_pk_bf16_f32 v178, v160, v161
	v_cvt_pk_bf16_f32 v179, v162, v163
	global_store_dwordx2 v197, v[178:179], s[56:57]
	v_add_u32_e32 v197, 0x8000, v197
	s_waitcnt lgkmcnt(1)
	v_max_f32_e32 v164, 0, v164
	v_max_f32_e32 v165, 0, v165
	v_max_f32_e32 v166, 0, v166
	v_max_f32_e32 v167, 0, v167
	v_mul_f32_e32 v164, v164, v164
	v_mul_f32_e32 v165, v165, v165
	v_mul_f32_e32 v166, v166, v166
	v_mul_f32_e32 v167, v167, v167
	v_cvt_pk_bf16_f32 v176, v164, v165
	v_cvt_pk_bf16_f32 v177, v166, v167
	global_store_dwordx2 v197, v[176:177], s[56:57]
	v_add_u32_e32 v197, 0x8000, v197
	s_waitcnt lgkmcnt(0)
	v_max_f32_e32 v168, 0, v168
	v_max_f32_e32 v169, 0, v169
	v_max_f32_e32 v170, 0, v170
	v_max_f32_e32 v171, 0, v171
	v_mul_f32_e32 v168, v168, v168
	v_mul_f32_e32 v169, v169, v169
	v_mul_f32_e32 v170, v170, v170
	v_mul_f32_e32 v171, v171, v171
	v_cvt_pk_bf16_f32 v178, v168, v169
	v_cvt_pk_bf16_f32 v179, v170, v171
	global_store_dwordx2 v197, v[178:179], s[56:57]
	v_add_u32_e32 v197, 0x8000, v197
	ds_write_b32 v203, v20 offset:0
	ds_write_b32 v203, v21 offset:272
	ds_write_b32 v203, v22 offset:544
	ds_write_b32 v203, v23 offset:816
	ds_write_b32 v203, v24 offset:64
	ds_write_b32 v203, v25 offset:336
	ds_write_b32 v203, v26 offset:608
	ds_write_b32 v203, v27 offset:880
	ds_write_b32 v203, v28 offset:128
	ds_write_b32 v203, v29 offset:400
	ds_write_b32 v203, v30 offset:672
	ds_write_b32 v203, v31 offset:944
	ds_write_b32 v203, v32 offset:192
	ds_write_b32 v203, v33 offset:464
	ds_write_b32 v203, v34 offset:736
	ds_write_b32 v203, v35 offset:1008
	s_waitcnt lgkmcnt(0)
	ds_read_b128 v[156:159], v204 offset:0
	ds_read_b128 v[160:163], v204 offset:1088
	ds_read_b128 v[164:167], v204 offset:2176
	ds_read_b128 v[168:171], v204 offset:3264
	s_waitcnt lgkmcnt(3)
	v_max_f32_e32 v156, 0, v156
	v_max_f32_e32 v157, 0, v157
	v_max_f32_e32 v158, 0, v158
	v_max_f32_e32 v159, 0, v159
	v_mul_f32_e32 v156, v156, v156
	v_mul_f32_e32 v157, v157, v157
	v_mul_f32_e32 v158, v158, v158
	v_mul_f32_e32 v159, v159, v159
	v_cvt_pk_bf16_f32 v176, v156, v157
	v_cvt_pk_bf16_f32 v177, v158, v159
	global_store_dwordx2 v197, v[176:177], s[56:57]
	v_add_u32_e32 v197, 0x8000, v197
	s_waitcnt lgkmcnt(2)
	v_max_f32_e32 v160, 0, v160
	v_max_f32_e32 v161, 0, v161
	v_max_f32_e32 v162, 0, v162
	v_max_f32_e32 v163, 0, v163
	v_mul_f32_e32 v160, v160, v160
	v_mul_f32_e32 v161, v161, v161
	v_mul_f32_e32 v162, v162, v162
	v_mul_f32_e32 v163, v163, v163
	v_cvt_pk_bf16_f32 v178, v160, v161
	v_cvt_pk_bf16_f32 v179, v162, v163
	global_store_dwordx2 v197, v[178:179], s[56:57]
	v_add_u32_e32 v197, 0x8000, v197
	s_waitcnt lgkmcnt(1)
	v_max_f32_e32 v164, 0, v164
	v_max_f32_e32 v165, 0, v165
	v_max_f32_e32 v166, 0, v166
	v_max_f32_e32 v167, 0, v167
	v_mul_f32_e32 v164, v164, v164
	v_mul_f32_e32 v165, v165, v165
	v_mul_f32_e32 v166, v166, v166
	v_mul_f32_e32 v167, v167, v167
	v_cvt_pk_bf16_f32 v176, v164, v165
	v_cvt_pk_bf16_f32 v177, v166, v167
	global_store_dwordx2 v197, v[176:177], s[56:57]
	v_add_u32_e32 v197, 0x8000, v197
	s_waitcnt lgkmcnt(0)
	v_max_f32_e32 v168, 0, v168
	v_max_f32_e32 v169, 0, v169
	v_max_f32_e32 v170, 0, v170
	v_max_f32_e32 v171, 0, v171
	v_mul_f32_e32 v168, v168, v168
	v_mul_f32_e32 v169, v169, v169
	v_mul_f32_e32 v170, v170, v170
	v_mul_f32_e32 v171, v171, v171
	v_cvt_pk_bf16_f32 v178, v168, v169
	v_cvt_pk_bf16_f32 v179, v170, v171
	global_store_dwordx2 v197, v[178:179], s[56:57]
	v_add_u32_e32 v197, 0x8000, v197
	ds_write_b32 v203, v36 offset:0
	ds_write_b32 v203, v37 offset:272
	ds_write_b32 v203, v38 offset:544
	ds_write_b32 v203, v39 offset:816
	ds_write_b32 v203, v40 offset:64
	ds_write_b32 v203, v41 offset:336
	ds_write_b32 v203, v42 offset:608
	ds_write_b32 v203, v43 offset:880
	ds_write_b32 v203, v44 offset:128
	ds_write_b32 v203, v45 offset:400
	ds_write_b32 v203, v46 offset:672
	ds_write_b32 v203, v47 offset:944
	ds_write_b32 v203, v48 offset:192
	ds_write_b32 v203, v49 offset:464
	ds_write_b32 v203, v50 offset:736
	ds_write_b32 v203, v51 offset:1008
	s_waitcnt lgkmcnt(0)
	ds_read_b128 v[156:159], v204 offset:0
	ds_read_b128 v[160:163], v204 offset:1088
	ds_read_b128 v[164:167], v204 offset:2176
	ds_read_b128 v[168:171], v204 offset:3264
	s_waitcnt lgkmcnt(3)
	v_max_f32_e32 v156, 0, v156
	v_max_f32_e32 v157, 0, v157
	v_max_f32_e32 v158, 0, v158
	v_max_f32_e32 v159, 0, v159
	v_mul_f32_e32 v156, v156, v156
	v_mul_f32_e32 v157, v157, v157
	v_mul_f32_e32 v158, v158, v158
	v_mul_f32_e32 v159, v159, v159
	v_cvt_pk_bf16_f32 v176, v156, v157
	v_cvt_pk_bf16_f32 v177, v158, v159
	global_store_dwordx2 v197, v[176:177], s[56:57]
	v_add_u32_e32 v197, 0x8000, v197
	s_waitcnt lgkmcnt(2)
	v_max_f32_e32 v160, 0, v160
	v_max_f32_e32 v161, 0, v161
	v_max_f32_e32 v162, 0, v162
	v_max_f32_e32 v163, 0, v163
	v_mul_f32_e32 v160, v160, v160
	v_mul_f32_e32 v161, v161, v161
	v_mul_f32_e32 v162, v162, v162
	v_mul_f32_e32 v163, v163, v163
	v_cvt_pk_bf16_f32 v178, v160, v161
	v_cvt_pk_bf16_f32 v179, v162, v163
	global_store_dwordx2 v197, v[178:179], s[56:57]
	v_add_u32_e32 v197, 0x8000, v197
	s_waitcnt lgkmcnt(1)
	v_max_f32_e32 v164, 0, v164
	v_max_f32_e32 v165, 0, v165
	v_max_f32_e32 v166, 0, v166
	v_max_f32_e32 v167, 0, v167
	v_mul_f32_e32 v164, v164, v164
	v_mul_f32_e32 v165, v165, v165
	v_mul_f32_e32 v166, v166, v166
	v_mul_f32_e32 v167, v167, v167
	v_cvt_pk_bf16_f32 v176, v164, v165
	v_cvt_pk_bf16_f32 v177, v166, v167
	global_store_dwordx2 v197, v[176:177], s[56:57]
	v_add_u32_e32 v197, 0x8000, v197
	s_waitcnt lgkmcnt(0)
	v_max_f32_e32 v168, 0, v168
	v_max_f32_e32 v169, 0, v169
	v_max_f32_e32 v170, 0, v170
	v_max_f32_e32 v171, 0, v171
	v_mul_f32_e32 v168, v168, v168
	v_mul_f32_e32 v169, v169, v169
	v_mul_f32_e32 v170, v170, v170
	v_mul_f32_e32 v171, v171, v171
	v_cvt_pk_bf16_f32 v178, v168, v169
	v_cvt_pk_bf16_f32 v179, v170, v171
	global_store_dwordx2 v197, v[178:179], s[56:57]
	v_add_u32_e32 v197, 0x8000, v197
	ds_write_b32 v203, v52 offset:0
	ds_write_b32 v203, v53 offset:272
	ds_write_b32 v203, v54 offset:544
	ds_write_b32 v203, v55 offset:816
	ds_write_b32 v203, v56 offset:64
	ds_write_b32 v203, v57 offset:336
	ds_write_b32 v203, v58 offset:608
	ds_write_b32 v203, v59 offset:880
	ds_write_b32 v203, v60 offset:128
	ds_write_b32 v203, v61 offset:400
	ds_write_b32 v203, v62 offset:672
	ds_write_b32 v203, v63 offset:944
	ds_write_b32 v203, v64 offset:192
	ds_write_b32 v203, v65 offset:464
	ds_write_b32 v203, v66 offset:736
	ds_write_b32 v203, v67 offset:1008
	s_waitcnt lgkmcnt(0)
	ds_read_b128 v[156:159], v204 offset:0
	ds_read_b128 v[160:163], v204 offset:1088
	ds_read_b128 v[164:167], v204 offset:2176
	ds_read_b128 v[168:171], v204 offset:3264
	s_waitcnt lgkmcnt(3)
	v_max_f32_e32 v156, 0, v156
	v_max_f32_e32 v157, 0, v157
	v_max_f32_e32 v158, 0, v158
	v_max_f32_e32 v159, 0, v159
	v_mul_f32_e32 v156, v156, v156
	v_mul_f32_e32 v157, v157, v157
	v_mul_f32_e32 v158, v158, v158
	v_mul_f32_e32 v159, v159, v159
	v_cvt_pk_bf16_f32 v176, v156, v157
	v_cvt_pk_bf16_f32 v177, v158, v159
	global_store_dwordx2 v197, v[176:177], s[56:57]
	v_add_u32_e32 v197, 0x8000, v197
	s_waitcnt lgkmcnt(2)
	v_max_f32_e32 v160, 0, v160
	v_max_f32_e32 v161, 0, v161
	v_max_f32_e32 v162, 0, v162
	v_max_f32_e32 v163, 0, v163
	v_mul_f32_e32 v160, v160, v160
	v_mul_f32_e32 v161, v161, v161
	v_mul_f32_e32 v162, v162, v162
	v_mul_f32_e32 v163, v163, v163
	v_cvt_pk_bf16_f32 v178, v160, v161
	v_cvt_pk_bf16_f32 v179, v162, v163
	global_store_dwordx2 v197, v[178:179], s[56:57]
	v_add_u32_e32 v197, 0x8000, v197
	s_waitcnt lgkmcnt(1)
	v_max_f32_e32 v164, 0, v164
	v_max_f32_e32 v165, 0, v165
	v_max_f32_e32 v166, 0, v166
	v_max_f32_e32 v167, 0, v167
	v_mul_f32_e32 v164, v164, v164
	v_mul_f32_e32 v165, v165, v165
	v_mul_f32_e32 v166, v166, v166
	v_mul_f32_e32 v167, v167, v167
	v_cvt_pk_bf16_f32 v176, v164, v165
	v_cvt_pk_bf16_f32 v177, v166, v167
	global_store_dwordx2 v197, v[176:177], s[56:57]
	v_add_u32_e32 v197, 0x8000, v197
	s_waitcnt lgkmcnt(0)
	v_max_f32_e32 v168, 0, v168
	v_max_f32_e32 v169, 0, v169
	v_max_f32_e32 v170, 0, v170
	v_max_f32_e32 v171, 0, v171
	v_mul_f32_e32 v168, v168, v168
	v_mul_f32_e32 v169, v169, v169
	v_mul_f32_e32 v170, v170, v170
	v_mul_f32_e32 v171, v171, v171
	v_cvt_pk_bf16_f32 v178, v168, v169
	v_cvt_pk_bf16_f32 v179, v170, v171
	global_store_dwordx2 v197, v[178:179], s[56:57]
	v_add_u32_e32 v197, 0x8000, v197
	ds_write_b32 v203, v68 offset:0
	ds_write_b32 v203, v69 offset:272
	ds_write_b32 v203, v70 offset:544
	ds_write_b32 v203, v71 offset:816
	ds_write_b32 v203, v72 offset:64
	ds_write_b32 v203, v73 offset:336
	ds_write_b32 v203, v74 offset:608
	ds_write_b32 v203, v75 offset:880
	ds_write_b32 v203, v76 offset:128
	ds_write_b32 v203, v77 offset:400
	ds_write_b32 v203, v78 offset:672
	ds_write_b32 v203, v79 offset:944
	ds_write_b32 v203, v80 offset:192
	ds_write_b32 v203, v81 offset:464
	ds_write_b32 v203, v82 offset:736
	ds_write_b32 v203, v83 offset:1008
	s_waitcnt lgkmcnt(0)
	ds_read_b128 v[156:159], v204 offset:0
	ds_read_b128 v[160:163], v204 offset:1088
	ds_read_b128 v[164:167], v204 offset:2176
	ds_read_b128 v[168:171], v204 offset:3264
	s_waitcnt lgkmcnt(3)
	v_max_f32_e32 v156, 0, v156
	v_max_f32_e32 v157, 0, v157
	v_max_f32_e32 v158, 0, v158
	v_max_f32_e32 v159, 0, v159
	v_mul_f32_e32 v156, v156, v156
	v_mul_f32_e32 v157, v157, v157
	v_mul_f32_e32 v158, v158, v158
	v_mul_f32_e32 v159, v159, v159
	v_cvt_pk_bf16_f32 v176, v156, v157
	v_cvt_pk_bf16_f32 v177, v158, v159
	global_store_dwordx2 v197, v[176:177], s[56:57]
	v_add_u32_e32 v197, 0x8000, v197
	s_waitcnt lgkmcnt(2)
	v_max_f32_e32 v160, 0, v160
	v_max_f32_e32 v161, 0, v161
	v_max_f32_e32 v162, 0, v162
	v_max_f32_e32 v163, 0, v163
	v_mul_f32_e32 v160, v160, v160
	v_mul_f32_e32 v161, v161, v161
	v_mul_f32_e32 v162, v162, v162
	v_mul_f32_e32 v163, v163, v163
	v_cvt_pk_bf16_f32 v178, v160, v161
	v_cvt_pk_bf16_f32 v179, v162, v163
	global_store_dwordx2 v197, v[178:179], s[56:57]
	v_add_u32_e32 v197, 0x8000, v197
	s_waitcnt lgkmcnt(1)
	v_max_f32_e32 v164, 0, v164
	v_max_f32_e32 v165, 0, v165
	v_max_f32_e32 v166, 0, v166
	v_max_f32_e32 v167, 0, v167
	v_mul_f32_e32 v164, v164, v164
	v_mul_f32_e32 v165, v165, v165
	v_mul_f32_e32 v166, v166, v166
	v_mul_f32_e32 v167, v167, v167
	v_cvt_pk_bf16_f32 v176, v164, v165
	v_cvt_pk_bf16_f32 v177, v166, v167
	global_store_dwordx2 v197, v[176:177], s[56:57]
	v_add_u32_e32 v197, 0x8000, v197
	s_waitcnt lgkmcnt(0)
	v_max_f32_e32 v168, 0, v168
	v_max_f32_e32 v169, 0, v169
	v_max_f32_e32 v170, 0, v170
	v_max_f32_e32 v171, 0, v171
	v_mul_f32_e32 v168, v168, v168
	v_mul_f32_e32 v169, v169, v169
	v_mul_f32_e32 v170, v170, v170
	v_mul_f32_e32 v171, v171, v171
	v_cvt_pk_bf16_f32 v178, v168, v169
	v_cvt_pk_bf16_f32 v179, v170, v171
	global_store_dwordx2 v197, v[178:179], s[56:57]
	v_add_u32_e32 v197, 0x8000, v197
	ds_write_b32 v203, v84 offset:0
	ds_write_b32 v203, v85 offset:272
	ds_write_b32 v203, v86 offset:544
	ds_write_b32 v203, v87 offset:816
	ds_write_b32 v203, v88 offset:64
	ds_write_b32 v203, v89 offset:336
	ds_write_b32 v203, v90 offset:608
	ds_write_b32 v203, v91 offset:880
	ds_write_b32 v203, v92 offset:128
	ds_write_b32 v203, v93 offset:400
	ds_write_b32 v203, v94 offset:672
	ds_write_b32 v203, v95 offset:944
	ds_write_b32 v203, v96 offset:192
	ds_write_b32 v203, v97 offset:464
	ds_write_b32 v203, v98 offset:736
	ds_write_b32 v203, v99 offset:1008
	s_waitcnt lgkmcnt(0)
	ds_read_b128 v[156:159], v204 offset:0
	ds_read_b128 v[160:163], v204 offset:1088
	ds_read_b128 v[164:167], v204 offset:2176
	ds_read_b128 v[168:171], v204 offset:3264
	s_waitcnt lgkmcnt(3)
	v_max_f32_e32 v156, 0, v156
	v_max_f32_e32 v157, 0, v157
	v_max_f32_e32 v158, 0, v158
	v_max_f32_e32 v159, 0, v159
	v_mul_f32_e32 v156, v156, v156
	v_mul_f32_e32 v157, v157, v157
	v_mul_f32_e32 v158, v158, v158
	v_mul_f32_e32 v159, v159, v159
	v_cvt_pk_bf16_f32 v176, v156, v157
	v_cvt_pk_bf16_f32 v177, v158, v159
	global_store_dwordx2 v197, v[176:177], s[56:57]
	v_add_u32_e32 v197, 0x8000, v197
	s_waitcnt lgkmcnt(2)
	v_max_f32_e32 v160, 0, v160
	v_max_f32_e32 v161, 0, v161
	v_max_f32_e32 v162, 0, v162
	v_max_f32_e32 v163, 0, v163
	v_mul_f32_e32 v160, v160, v160
	v_mul_f32_e32 v161, v161, v161
	v_mul_f32_e32 v162, v162, v162
	v_mul_f32_e32 v163, v163, v163
	v_cvt_pk_bf16_f32 v178, v160, v161
	v_cvt_pk_bf16_f32 v179, v162, v163
	global_store_dwordx2 v197, v[178:179], s[56:57]
	v_add_u32_e32 v197, 0x8000, v197
	s_waitcnt lgkmcnt(1)
	v_max_f32_e32 v164, 0, v164
	v_max_f32_e32 v165, 0, v165
	v_max_f32_e32 v166, 0, v166
	v_max_f32_e32 v167, 0, v167
	v_mul_f32_e32 v164, v164, v164
	v_mul_f32_e32 v165, v165, v165
	v_mul_f32_e32 v166, v166, v166
	v_mul_f32_e32 v167, v167, v167
	v_cvt_pk_bf16_f32 v176, v164, v165
	v_cvt_pk_bf16_f32 v177, v166, v167
	global_store_dwordx2 v197, v[176:177], s[56:57]
	v_add_u32_e32 v197, 0x8000, v197
	s_waitcnt lgkmcnt(0)
	v_max_f32_e32 v168, 0, v168
	v_max_f32_e32 v169, 0, v169
	v_max_f32_e32 v170, 0, v170
	v_max_f32_e32 v171, 0, v171
	v_mul_f32_e32 v168, v168, v168
	v_mul_f32_e32 v169, v169, v169
	v_mul_f32_e32 v170, v170, v170
	v_mul_f32_e32 v171, v171, v171
	v_cvt_pk_bf16_f32 v178, v168, v169
	v_cvt_pk_bf16_f32 v179, v170, v171
	global_store_dwordx2 v197, v[178:179], s[56:57]
	v_add_u32_e32 v197, 0x8000, v197
	v_mov_b32_e32 v4, 0
	v_mov_b32_e32 v5, 0
	v_mov_b32_e32 v6, 0
	v_mov_b32_e32 v7, 0
	v_mov_b32_e32 v8, 0
	v_mov_b32_e32 v9, 0
	v_mov_b32_e32 v10, 0
	v_mov_b32_e32 v11, 0
	v_mov_b32_e32 v12, 0
	v_mov_b32_e32 v13, 0
	v_mov_b32_e32 v14, 0
	v_mov_b32_e32 v15, 0
	v_mov_b32_e32 v16, 0
	v_mov_b32_e32 v17, 0
	v_mov_b32_e32 v18, 0
	v_mov_b32_e32 v19, 0
	v_mov_b32_e32 v20, 0
	v_mov_b32_e32 v21, 0
	v_mov_b32_e32 v22, 0
	v_mov_b32_e32 v23, 0
	v_mov_b32_e32 v24, 0
	v_mov_b32_e32 v25, 0
	v_mov_b32_e32 v26, 0
	v_mov_b32_e32 v27, 0
	v_mov_b32_e32 v28, 0
	v_mov_b32_e32 v29, 0
	v_mov_b32_e32 v30, 0
	v_mov_b32_e32 v31, 0
	v_mov_b32_e32 v32, 0
	v_mov_b32_e32 v33, 0
	v_mov_b32_e32 v34, 0
	v_mov_b32_e32 v35, 0
	v_mov_b32_e32 v36, 0
	v_mov_b32_e32 v37, 0
	v_mov_b32_e32 v38, 0
	v_mov_b32_e32 v39, 0
	v_mov_b32_e32 v40, 0
	v_mov_b32_e32 v41, 0
	v_mov_b32_e32 v42, 0
	v_mov_b32_e32 v43, 0
	v_mov_b32_e32 v44, 0
	v_mov_b32_e32 v45, 0
	v_mov_b32_e32 v46, 0
	v_mov_b32_e32 v47, 0
	v_mov_b32_e32 v48, 0
	v_mov_b32_e32 v49, 0
	v_mov_b32_e32 v50, 0
	v_mov_b32_e32 v51, 0
	v_mov_b32_e32 v52, 0
	v_mov_b32_e32 v53, 0
	v_mov_b32_e32 v54, 0
	v_mov_b32_e32 v55, 0
	v_mov_b32_e32 v56, 0
	v_mov_b32_e32 v57, 0
	v_mov_b32_e32 v58, 0
	v_mov_b32_e32 v59, 0
	v_mov_b32_e32 v60, 0
	v_mov_b32_e32 v61, 0
	v_mov_b32_e32 v62, 0
	v_mov_b32_e32 v63, 0
	v_mov_b32_e32 v64, 0
	v_mov_b32_e32 v65, 0
	v_mov_b32_e32 v66, 0
	v_mov_b32_e32 v67, 0
	v_mov_b32_e32 v68, 0
	v_mov_b32_e32 v69, 0
	v_mov_b32_e32 v70, 0
	v_mov_b32_e32 v71, 0
	v_mov_b32_e32 v72, 0
	v_mov_b32_e32 v73, 0
	v_mov_b32_e32 v74, 0
	v_mov_b32_e32 v75, 0
	v_mov_b32_e32 v76, 0
	v_mov_b32_e32 v77, 0
	v_mov_b32_e32 v78, 0
	v_mov_b32_e32 v79, 0
	v_mov_b32_e32 v80, 0
	v_mov_b32_e32 v81, 0
	v_mov_b32_e32 v82, 0
	v_mov_b32_e32 v83, 0
	v_mov_b32_e32 v84, 0
	v_mov_b32_e32 v85, 0
	v_mov_b32_e32 v86, 0
	v_mov_b32_e32 v87, 0
	v_mov_b32_e32 v88, 0
	v_mov_b32_e32 v89, 0
	v_mov_b32_e32 v90, 0
	v_mov_b32_e32 v91, 0
	v_mov_b32_e32 v92, 0
	v_mov_b32_e32 v93, 0
	v_mov_b32_e32 v94, 0
	v_mov_b32_e32 v95, 0
	v_mov_b32_e32 v96, 0
	v_mov_b32_e32 v97, 0
	v_mov_b32_e32 v98, 0
	v_mov_b32_e32 v99, 0
	s_mov_b32 s34, 0
	s_add_u32 s35, s35, s52
	s_cmp_ge_u32 s31, s30
	s_cbranch_scc1 .Lgm_f1_exit
	s_waitcnt vmcnt(31)
	s_branch .Lgm_f1_loop
